# ssd_m2 X-operand conv+SiLU rewritten by hand: all 512 threads (8 channels x 2 rows each) instead of 128 threads x 8 rows
# speedup vs baseline: 1.0038x; 1.0038x over previous
; #define LAS __attribute__((address_space(3)))
; #define TIDX opaque_tid()
; __device__ __forceinline__ u32x4 pack8(const float* f) { u32x4 w; w.x = pk2(f[0], f[1]); w.y = pk2(f[2], f[3]); w.z = pk2(f[4], f[5]); w.w = pk2(f[6], f[7]); return w; }
; template <class CM, class F>
; __device__ __forceinline__ void conv64(const bf16_t* proj, int row0, int tseq0, int pc0, const float* cw, const float* cb, int C, int nchunks, CM&& chmap, F&& emit) {
;     for (int u = TIDX; u < nchunks * 8; u += 512) {
;         const int q = u % nchunks, seg = u / nchunks, c = chmap(q), j0 = seg * 8;
;         const bf16_t* src = proj + (size_t)(row0 + j0) * NPROJ + pc0 + c;
;         u32x4 raw[11];
;         if (tseq0 + j0 == 0) { raw[0] = (u32x4){0u, 0u, 0u, 0u}; raw[1] = raw[0]; raw[2] = raw[0]; }
;         else { raw[0] = *(const u32x4*)(src - 3 * NPROJ); raw[1] = *(const u32x4*)(src - 2 * NPROJ); raw[2] = *(const u32x4*)(src - NPROJ); }
; #pragma unroll
;         for (int j = 0; j < 8; ++j) raw[3 + j] = *(const u32x4*)(src + (size_t)j * NPROJ);
;         float w0[8], w1[8], w2[8], w3[8], bb[8];
; #pragma unroll
;         for (int e = 0; e < 8; ++e) { w0[e] = cw[c + e]; w1[e] = cw[C + c + e]; w2[e] = cw[2 * C + c + e]; w3[e] = cw[3 * C + c + e]; bb[e] = cb[c + e]; }
;         float h3[8], h2[8], h1[8];
;         unpack8(raw[0], h3); unpack8(raw[1], h2); unpack8(raw[2], h1);
; #pragma unroll
;         for (int j = 0; j < 8; ++j) {
;             float cur[8], y[8];
;             unpack8(raw[3 + j], cur);
; #pragma unroll
;             for (int e = 0; e < 8; ++e) y[e] = bb[e] + w0[e] * h3[e] + w1[e] * h2[e] + w2[e] * h1[e] + w3[e] * cur[e];
;             emit(j0 + j, q, c, y);
; #pragma unroll
;             for (int e = 0; e < 8; ++e) { h3[e] = h2[e]; h2[e] = h1[e]; h1[e] = cur[e]; }
;         }
; __device__ void ssd_m2(const Params& p, LAS unsigned char* lds, int l, int b, int c, int g) {
;     ...
;         conv64(proj, row0, c * 64, PC_XBC, cw, cb, 1024, 16, [hbase](int q) { return hbase * 64 + q * 8; },
;                [&](int j, int q, int ch, float* y) {
;                    float s[8];
; #pragma unroll
;                    for (int e = 0; e < 8; ++e) s[e] = siluf_(y[e]);
;                    *(LAS u32x4*)((LAS bf16_t*)(lds + PB + (q >> 3) * HB + 9216) + j * 72 + (q & 7) * 8) = pack8(s);
;                });
.LBB0_343:
	s_or_b64 exec, exec, s[0:1]
	s_mov_b64 s[0:1], exec
	v_and_b32_e32 v43, 15, v163
	v_lshrrev_b32_e32 v0, 4, v163
	v_lshlrev_b32_e32 v0, 1, v0
	s_lshl_b32 s36, s96, 8
	v_lshl_add_u32 v112, v43, 3, s36
	v_add_u32_e32 v113, s30, v0
	v_add_u32_e32 v104, s26, v0
	v_add_u32_e32 v104, -3, v104
	v_ashrrev_i32_e32 v105, 31, v104
	v_lshlrev_b64 v[104:105], 13, v[104:105]
	v_lshl_add_u64 v[104:105], s[34:35], 0, v[104:105]
	v_lshlrev_b32_e32 v114, 1, v112
	v_mov_b32_e32 v115, 0
	v_lshl_add_u64 v[104:105], v[104:105], 0, v[114:115]
	s_mov_b64 s[40:41], 0x1800
	v_lshl_add_u64 v[104:105], v[104:105], 0, s[40:41]
	v_lshlrev_b32_e32 v114, 2, v112
	v_lshl_add_u64 v[106:107], s[22:23], 0, v[114:115]
	v_lshl_add_u64 v[108:109], s[38:39], 0, v[114:115]
	v_mov_b32_e32 v44, 0
	v_mov_b32_e32 v45, 0
	v_mov_b32_e32 v46, 0
	v_mov_b32_e32 v47, 0
	v_mov_b32_e32 v48, 0
	v_mov_b32_e32 v49, 0
	v_mov_b32_e32 v50, 0
	v_mov_b32_e32 v51, 0
	v_mov_b32_e32 v52, 0
	v_mov_b32_e32 v53, 0
	v_mov_b32_e32 v54, 0
	v_mov_b32_e32 v55, 0
	s_mov_b64 s[40:41], 0x2000
	v_cmp_le_i32_e32 vcc, 3, v113
	s_and_saveexec_b64 s[36:37], vcc
	global_load_dwordx4 v[44:47], v[104:105], off
	s_or_b64 exec, exec, s[36:37]
	v_lshl_add_u64 v[104:105], v[104:105], 0, s[40:41]
	v_cmp_le_i32_e32 vcc, 2, v113
	s_and_saveexec_b64 s[36:37], vcc
	global_load_dwordx4 v[48:51], v[104:105], off
	s_or_b64 exec, exec, s[36:37]
	v_lshl_add_u64 v[104:105], v[104:105], 0, s[40:41]
	v_cmp_le_i32_e32 vcc, 1, v113
	s_and_saveexec_b64 s[36:37], vcc
	global_load_dwordx4 v[52:55], v[104:105], off
	s_or_b64 exec, exec, s[36:37]
	v_lshl_add_u64 v[104:105], v[104:105], 0, s[40:41]
	global_load_dwordx4 v[56:59], v[104:105], off
	v_lshl_add_u64 v[104:105], v[104:105], 0, s[40:41]
	global_load_dwordx4 v[60:63], v[104:105], off
	s_mov_b64 s[40:41], 0x1000
	global_load_dwordx4 v[64:67], v[106:107], off
	global_load_dwordx4 v[68:71], v[106:107], off offset:16
	v_lshl_add_u64 v[106:107], v[106:107], 0, s[40:41]
	global_load_dwordx4 v[72:75], v[106:107], off
	global_load_dwordx4 v[76:79], v[106:107], off offset:16
	v_lshl_add_u64 v[106:107], v[106:107], 0, s[40:41]
	global_load_dwordx4 v[80:83], v[106:107], off
	global_load_dwordx4 v[84:87], v[106:107], off offset:16
	v_lshl_add_u64 v[106:107], v[106:107], 0, s[40:41]
	global_load_dwordx4 v[88:91], v[106:107], off
	global_load_dwordx4 v[92:95], v[106:107], off offset:16
	global_load_dwordx4 v[96:99], v[108:109], off
	global_load_dwordx4 v[100:103], v[108:109], off offset:16
	v_lshrrev_b32_e32 v116, 3, v43
	v_mul_u32_u24_e32 v116, 0x8c00, v116
	v_mul_u32_u24_e32 v114, 0x90, v0
	v_and_b32_e32 v115, 7, v43
	v_lshl_add_u32 v114, v115, 4, v114
	v_add_u32_e32 v116, v116, v114
	s_waitcnt vmcnt(0)
	v_lshlrev_b32_e32 v114, 16, v44
	v_mul_f32_e32 v114, v64, v114
	v_add_f32_e32 v112, v96, v114
	v_lshlrev_b32_e32 v114, 16, v48
	v_mul_f32_e32 v114, v72, v114
	v_add_f32_e32 v112, v112, v114
	v_lshlrev_b32_e32 v114, 16, v52
	v_mul_f32_e32 v114, v80, v114
	v_add_f32_e32 v112, v112, v114
	v_lshlrev_b32_e32 v114, 16, v56
	v_mul_f32_e32 v114, v88, v114
	v_add_f32_e32 v112, v112, v114
	v_lshlrev_b32_e32 v115, 16, v48
	v_mul_f32_e32 v115, v64, v115
	v_add_f32_e32 v113, v96, v115
	v_lshlrev_b32_e32 v115, 16, v52
	v_mul_f32_e32 v115, v72, v115
	v_add_f32_e32 v113, v113, v115
	v_lshlrev_b32_e32 v115, 16, v56
	v_mul_f32_e32 v115, v80, v115
	v_add_f32_e32 v113, v113, v115
	v_lshlrev_b32_e32 v115, 16, v60
	v_mul_f32_e32 v115, v88, v115
	v_add_f32_e32 v113, v113, v115
	v_mul_f32_e32 v114, 0xbfb8aa3b, v112
	v_mul_f32_e32 v115, 0xbfb8aa3b, v113
	v_exp_f32_e32 v114, v114
	v_exp_f32_e32 v115, v115
	s_nop 0
	v_add_f32_e32 v114, 1.0, v114
	v_add_f32_e32 v115, 1.0, v115
	v_rcp_f32_e32 v114, v114
	v_rcp_f32_e32 v115, v115
	s_nop 0
	v_mul_f32_e32 v117, v112, v114
	v_mul_f32_e32 v43, v113, v115
	v_and_b32_e32 v114, 0xffff0000, v44
	v_mul_f32_e32 v114, v65, v114
	v_add_f32_e32 v112, v97, v114
	v_and_b32_e32 v114, 0xffff0000, v48
	v_mul_f32_e32 v114, v73, v114
	v_add_f32_e32 v112, v112, v114
	v_and_b32_e32 v114, 0xffff0000, v52
	v_mul_f32_e32 v114, v81, v114
	v_add_f32_e32 v112, v112, v114
	v_and_b32_e32 v114, 0xffff0000, v56
	v_mul_f32_e32 v114, v89, v114
	v_add_f32_e32 v112, v112, v114
	v_and_b32_e32 v115, 0xffff0000, v48
	v_mul_f32_e32 v115, v65, v115
	v_add_f32_e32 v113, v97, v115
	v_and_b32_e32 v115, 0xffff0000, v52
	v_mul_f32_e32 v115, v73, v115
	v_add_f32_e32 v113, v113, v115
	v_and_b32_e32 v115, 0xffff0000, v56
	v_mul_f32_e32 v115, v81, v115
	v_add_f32_e32 v113, v113, v115
	v_and_b32_e32 v115, 0xffff0000, v60
	v_mul_f32_e32 v115, v89, v115
	v_add_f32_e32 v113, v113, v115
	v_mul_f32_e32 v114, 0xbfb8aa3b, v112
	v_mul_f32_e32 v115, 0xbfb8aa3b, v113
	v_exp_f32_e32 v114, v114
	v_exp_f32_e32 v115, v115
	s_nop 0
	v_add_f32_e32 v114, 1.0, v114
	v_add_f32_e32 v115, 1.0, v115
	v_rcp_f32_e32 v114, v114
	v_rcp_f32_e32 v115, v115
	s_nop 0
	v_mul_f32_e32 v112, v112, v114
	v_mul_f32_e32 v113, v113, v115
	v_cvt_pk_bf16_f32 v104, v117, v112
	v_cvt_pk_bf16_f32 v108, v43, v113
	v_lshlrev_b32_e32 v114, 16, v45
	v_mul_f32_e32 v114, v66, v114
	v_add_f32_e32 v112, v98, v114
	v_lshlrev_b32_e32 v114, 16, v49
	v_mul_f32_e32 v114, v74, v114
	v_add_f32_e32 v112, v112, v114
	v_lshlrev_b32_e32 v114, 16, v53
	v_mul_f32_e32 v114, v82, v114
	v_add_f32_e32 v112, v112, v114
	v_lshlrev_b32_e32 v114, 16, v57
	v_mul_f32_e32 v114, v90, v114
	v_add_f32_e32 v112, v112, v114
	v_lshlrev_b32_e32 v115, 16, v49
	v_mul_f32_e32 v115, v66, v115
	v_add_f32_e32 v113, v98, v115
	v_lshlrev_b32_e32 v115, 16, v53
	v_mul_f32_e32 v115, v74, v115
	v_add_f32_e32 v113, v113, v115
	v_lshlrev_b32_e32 v115, 16, v57
	v_mul_f32_e32 v115, v82, v115
	v_add_f32_e32 v113, v113, v115
; #define LAS __attribute__((address_space(3)))
; __device__ __forceinline__ u32x4 pack8(const float* f) { u32x4 w; w.x = pk2(f[0], f[1]); w.y = pk2(f[2], f[3]); w.z = pk2(f[4], f[5]); w.w = pk2(f[6], f[7]); return w; }
; __device__ __forceinline__ float siluf_(float x) { return x * __builtin_amdgcn_rcpf(1.f + fexp_(-x)); }
; template <class CM, class F>
; __device__ __forceinline__ void conv64(const bf16_t* proj, int row0, int tseq0, int pc0, const float* cw, const float* cb, int C, int nchunks, CM&& chmap, F&& emit) {
;     ...
;             for (int e = 0; e < 8; ++e) y[e] = bb[e] + w0[e] * h3[e] + w1[e] * h2[e] + w2[e] * h1[e] + w3[e] * cur[e];
;             emit(j0 + j, q, c, y);
; __device__ void ssd_m2(const Params& p, LAS unsigned char* lds, int l, int b, int c, int g) {
;     ...
;                    for (int e = 0; e < 8; ++e) s[e] = siluf_(y[e]);
;                    *(LAS u32x4*)((LAS bf16_t*)(lds + PB + (q >> 3) * HB + 9216) + j * 72 + (q & 7) * 8) = pack8(s);
	v_lshlrev_b32_e32 v115, 16, v61
	v_mul_f32_e32 v115, v90, v115
	v_add_f32_e32 v113, v113, v115
	v_mul_f32_e32 v114, 0xbfb8aa3b, v112
	v_mul_f32_e32 v115, 0xbfb8aa3b, v113
	v_exp_f32_e32 v114, v114
	v_exp_f32_e32 v115, v115
	s_nop 0
	v_add_f32_e32 v114, 1.0, v114
	v_add_f32_e32 v115, 1.0, v115
	v_rcp_f32_e32 v114, v114
	v_rcp_f32_e32 v115, v115
	s_nop 0
	v_mul_f32_e32 v117, v112, v114
	v_mul_f32_e32 v43, v113, v115
	v_and_b32_e32 v114, 0xffff0000, v45
	v_mul_f32_e32 v114, v67, v114
	v_add_f32_e32 v112, v99, v114
	v_and_b32_e32 v114, 0xffff0000, v49
	v_mul_f32_e32 v114, v75, v114
	v_add_f32_e32 v112, v112, v114
	v_and_b32_e32 v114, 0xffff0000, v53
	v_mul_f32_e32 v114, v83, v114
	v_add_f32_e32 v112, v112, v114
	v_and_b32_e32 v114, 0xffff0000, v57
	v_mul_f32_e32 v114, v91, v114
	v_add_f32_e32 v112, v112, v114
	v_and_b32_e32 v115, 0xffff0000, v49
	v_mul_f32_e32 v115, v67, v115
	v_add_f32_e32 v113, v99, v115
	v_and_b32_e32 v115, 0xffff0000, v53
	v_mul_f32_e32 v115, v75, v115
	v_add_f32_e32 v113, v113, v115
	v_and_b32_e32 v115, 0xffff0000, v57
	v_mul_f32_e32 v115, v83, v115
	v_add_f32_e32 v113, v113, v115
	v_and_b32_e32 v115, 0xffff0000, v61
	v_mul_f32_e32 v115, v91, v115
	v_add_f32_e32 v113, v113, v115
	v_mul_f32_e32 v114, 0xbfb8aa3b, v112
	v_mul_f32_e32 v115, 0xbfb8aa3b, v113
	v_exp_f32_e32 v114, v114
	v_exp_f32_e32 v115, v115
	s_nop 0
	v_add_f32_e32 v114, 1.0, v114
	v_add_f32_e32 v115, 1.0, v115
	v_rcp_f32_e32 v114, v114
	v_rcp_f32_e32 v115, v115
	s_nop 0
	v_mul_f32_e32 v112, v112, v114
	v_mul_f32_e32 v113, v113, v115
	v_cvt_pk_bf16_f32 v105, v117, v112
	v_cvt_pk_bf16_f32 v109, v43, v113
	v_lshlrev_b32_e32 v114, 16, v46
	v_mul_f32_e32 v114, v68, v114
	v_add_f32_e32 v112, v100, v114
	v_lshlrev_b32_e32 v114, 16, v50
	v_mul_f32_e32 v114, v76, v114
	v_add_f32_e32 v112, v112, v114
	v_lshlrev_b32_e32 v114, 16, v54
	v_mul_f32_e32 v114, v84, v114
	v_add_f32_e32 v112, v112, v114
	v_lshlrev_b32_e32 v114, 16, v58
	v_mul_f32_e32 v114, v92, v114
	v_add_f32_e32 v112, v112, v114
	v_lshlrev_b32_e32 v115, 16, v50
	v_mul_f32_e32 v115, v68, v115
	v_add_f32_e32 v113, v100, v115
	v_lshlrev_b32_e32 v115, 16, v54
	v_mul_f32_e32 v115, v76, v115
	v_add_f32_e32 v113, v113, v115
	v_lshlrev_b32_e32 v115, 16, v58
	v_mul_f32_e32 v115, v84, v115
	v_add_f32_e32 v113, v113, v115
	v_lshlrev_b32_e32 v115, 16, v62
	v_mul_f32_e32 v115, v92, v115
	v_add_f32_e32 v113, v113, v115
	v_mul_f32_e32 v114, 0xbfb8aa3b, v112
	v_mul_f32_e32 v115, 0xbfb8aa3b, v113
	v_exp_f32_e32 v114, v114
	v_exp_f32_e32 v115, v115
	s_nop 0
	v_add_f32_e32 v114, 1.0, v114
	v_add_f32_e32 v115, 1.0, v115
	v_rcp_f32_e32 v114, v114
	v_rcp_f32_e32 v115, v115
	s_nop 0
	v_mul_f32_e32 v117, v112, v114
	v_mul_f32_e32 v43, v113, v115
	v_and_b32_e32 v114, 0xffff0000, v46
	v_mul_f32_e32 v114, v69, v114
	v_add_f32_e32 v112, v101, v114
	v_and_b32_e32 v114, 0xffff0000, v50
	v_mul_f32_e32 v114, v77, v114
	v_add_f32_e32 v112, v112, v114
	v_and_b32_e32 v114, 0xffff0000, v54
	v_mul_f32_e32 v114, v85, v114
	v_add_f32_e32 v112, v112, v114
	v_and_b32_e32 v114, 0xffff0000, v58
	v_mul_f32_e32 v114, v93, v114
	v_add_f32_e32 v112, v112, v114
	v_and_b32_e32 v115, 0xffff0000, v50
	v_mul_f32_e32 v115, v69, v115
	v_add_f32_e32 v113, v101, v115
	v_and_b32_e32 v115, 0xffff0000, v54
	v_mul_f32_e32 v115, v77, v115
	v_add_f32_e32 v113, v113, v115
	v_and_b32_e32 v115, 0xffff0000, v58
	v_mul_f32_e32 v115, v85, v115
	v_add_f32_e32 v113, v113, v115
	v_and_b32_e32 v115, 0xffff0000, v62
	v_mul_f32_e32 v115, v93, v115
	v_add_f32_e32 v113, v113, v115
	v_mul_f32_e32 v114, 0xbfb8aa3b, v112
	v_mul_f32_e32 v115, 0xbfb8aa3b, v113
	v_exp_f32_e32 v114, v114
	v_exp_f32_e32 v115, v115
	s_nop 0
	v_add_f32_e32 v114, 1.0, v114
	v_add_f32_e32 v115, 1.0, v115
	v_rcp_f32_e32 v114, v114
	v_rcp_f32_e32 v115, v115
	s_nop 0
	v_mul_f32_e32 v112, v112, v114
	v_mul_f32_e32 v113, v113, v115
	v_cvt_pk_bf16_f32 v106, v117, v112
	v_cvt_pk_bf16_f32 v110, v43, v113
	v_lshlrev_b32_e32 v114, 16, v47
	v_mul_f32_e32 v114, v70, v114
	v_add_f32_e32 v112, v102, v114
	v_lshlrev_b32_e32 v114, 16, v51
	v_mul_f32_e32 v114, v78, v114
	v_add_f32_e32 v112, v112, v114
	v_lshlrev_b32_e32 v114, 16, v55
	v_mul_f32_e32 v114, v86, v114
	v_add_f32_e32 v112, v112, v114
	v_lshlrev_b32_e32 v114, 16, v59
	v_mul_f32_e32 v114, v94, v114
	v_add_f32_e32 v112, v112, v114
	v_lshlrev_b32_e32 v115, 16, v51
	v_mul_f32_e32 v115, v70, v115
	v_add_f32_e32 v113, v102, v115
	v_lshlrev_b32_e32 v115, 16, v55
	v_mul_f32_e32 v115, v78, v115
	v_add_f32_e32 v113, v113, v115
	v_lshlrev_b32_e32 v115, 16, v59
	v_mul_f32_e32 v115, v86, v115
	v_add_f32_e32 v113, v113, v115
	v_lshlrev_b32_e32 v115, 16, v63
	v_mul_f32_e32 v115, v94, v115
	v_add_f32_e32 v113, v113, v115
	v_mul_f32_e32 v114, 0xbfb8aa3b, v112
	v_mul_f32_e32 v115, 0xbfb8aa3b, v113
	v_exp_f32_e32 v114, v114
	v_exp_f32_e32 v115, v115
	s_nop 0
	v_add_f32_e32 v114, 1.0, v114
	v_add_f32_e32 v115, 1.0, v115
	v_rcp_f32_e32 v114, v114
	v_rcp_f32_e32 v115, v115
	s_nop 0
	v_mul_f32_e32 v117, v112, v114
	v_mul_f32_e32 v43, v113, v115
	v_and_b32_e32 v114, 0xffff0000, v47
	v_mul_f32_e32 v114, v71, v114
	v_add_f32_e32 v112, v103, v114
	v_and_b32_e32 v114, 0xffff0000, v51
	v_mul_f32_e32 v114, v79, v114
	v_add_f32_e32 v112, v112, v114
	v_and_b32_e32 v114, 0xffff0000, v55
	v_mul_f32_e32 v114, v87, v114
	v_add_f32_e32 v112, v112, v114
	v_and_b32_e32 v114, 0xffff0000, v59
	v_mul_f32_e32 v114, v95, v114
	v_add_f32_e32 v112, v112, v114
	v_and_b32_e32 v115, 0xffff0000, v51
	v_mul_f32_e32 v115, v71, v115
	v_add_f32_e32 v113, v103, v115
	v_and_b32_e32 v115, 0xffff0000, v55
	v_mul_f32_e32 v115, v79, v115
	v_add_f32_e32 v113, v113, v115
	v_and_b32_e32 v115, 0xffff0000, v59
	v_mul_f32_e32 v115, v87, v115
	v_add_f32_e32 v113, v113, v115
	v_and_b32_e32 v115, 0xffff0000, v63
	v_mul_f32_e32 v115, v95, v115
	v_add_f32_e32 v113, v113, v115
	v_mul_f32_e32 v114, 0xbfb8aa3b, v112
	v_mul_f32_e32 v115, 0xbfb8aa3b, v113
	v_exp_f32_e32 v114, v114
	v_exp_f32_e32 v115, v115
	s_nop 0
	v_add_f32_e32 v114, 1.0, v114
	v_add_f32_e32 v115, 1.0, v115
	v_rcp_f32_e32 v114, v114
	v_rcp_f32_e32 v115, v115
	s_nop 0
	v_mul_f32_e32 v112, v112, v114
	v_mul_f32_e32 v113, v113, v115
	v_cvt_pk_bf16_f32 v107, v117, v112
	v_cvt_pk_bf16_f32 v111, v43, v113
	ds_write_b128 v116, v[104:107] offset:44032
	ds_write_b128 v116, v[108:111] offset:44176
	s_waitcnt lgkmcnt(0)
; #define LAS __attribute__((address_space(3)))
; __device__ __forceinline__ unsigned pk2(float lo, float hi) { unsigned r; asm volatile("v_cvt_pk_bf16_f32 %0, %1, %2" : "=v"(r) : "v"(lo), "v"(hi)); return r; }
; __device__ __forceinline__ float fexp_(float x) { return __builtin_amdgcn_exp2f(x * 1.44269504089f); }
; #define MFMA(X, Y, C) __builtin_amdgcn_mfma_f32_16x16x32_bf16((X), (Y), (C), 0, 0, 0)
; __device__ void ssd_m2(const Params& p, LAS unsigned char* lds, int l, int b, int c, int g) {
;     ...
;         for (int i = 0; i < 4; ++i) { const int id = tid + 512 * i, h2 = id >> 10, pp = (id >> 4) & 63, nc = id & 15;
;             *(LAS u32x4*)((LAS bf16_t*)(lds + PB + h2 * HB + 18432) + pp * 136 + nc * 8) = *(const u32x4*)(sp + ((size_t)((b * 8 + hbase + h2) * NCH + c)) * 8192 + pp * 128 + nc * 8); }
;         __syncthreads();
;         const int h = hbase + hh, hl = 2 * pr + hh;
;         LAS bf16_t* P = (LAS bf16_t*)(lds + PB + hh * HB); LAS bf16_t* X = P + 64 * 72; LAS bf16_t* S = (LAS bf16_t*)(lds + PB + hh * HB + 18432);
;         bf16x8 Yc[4];
; #pragma unroll
;         for (int kk = 0; kk < 4; ++kk) Yc[kk] = frag_row(Cm, 136, i0, kk * 32, fr, fq);
;         const float cumi = cum[hl * 64 + irow];
; #pragma unroll
;         for (int jh = 0; jh < 2; ++jh) {
;             bf16x8 Xb[2][4]; f32x4 cj[2], dj[2];
; #pragma unroll
;             for (int q = 0; q < 2; ++q) {
; #pragma unroll
;                 for (int kk = 0; kk < 4; ++kk) Xb[q][kk] = frag_row(Bm, 136, (2 * jh + q) * 16, kk * 32, fr, fq);
;                 cj[q] = *(const LAS f32x4*)(cum + hl * 64 + (2 * jh + q) * 16 + 4 * fq); dj[q] = *(const LAS f32x4*)(dtv + hl * 64 + (2 * jh + q) * 16 + 4 * fq);
;             }
; #pragma unroll
;             for (int q = 0; q < 2; ++q) {
;                 const int jt = 2 * jh + q;
;                 f32x4 sc = {0.f, 0.f, 0.f, 0.f};
; #pragma unroll
;                 for (int kk = 0; kk < 4; ++kk) sc = MFMA(Xb[q][kk], Yc[kk], sc);
;                 float v[4];
; #pragma unroll
;                 for (int i = 0; i < 4; ++i) { const int j = jt * 16 + 4 * fq + i; v[i] = j <= irow ? sc[i] * fexp_(cumi - cj[q][i]) * dj[q][i] : 0.f; }
;                 u32x2 w; w.x = pk2(v[0], v[1]); w.y = pk2(v[2], v[3]);
;                 *(LAS u32x2*)(P + irow * 72 + jt * 16 + 4 * fq) = w;
;             }
;         }
.LBB0_348:
	s_or_b64 exec, exec, s[0:1]
	v_lshlrev_b32_e32 v62, 3, v127
	v_and_b32_e32 v0, 0x78, v62
	s_lshl_b32 s24, s44, 3
	v_lshlrev_b32_e32 v132, 1, v0
	v_add_u32_e32 v0, 0x200, v127
	s_or_b32 s0, s94, s24
	v_ashrrev_i32_e32 v195, 10, v0
	v_bfe_u32 v203, v0, 4, 6
	v_add_u32_e32 v0, s0, v195
	v_lshl_or_b32 v4, v0, 5, s95
	v_add_u32_e32 v0, 0x400, v127
	v_ashrrev_i32_e32 v197, 10, v127
	v_ashrrev_i32_e32 v196, 10, v0
	v_add_u32_e32 v2, s0, v197
	v_add_u32_e32 v0, s0, v196
	v_lshl_or_b32 v2, v2, 5, s95
	v_lshl_or_b32 v12, v0, 5, s95
	v_ashrrev_i32_e32 v3, 31, v2
	v_ashrrev_i32_e32 v13, 31, v12
	v_add_u32_e32 v0, 0x600, v127
	v_bfe_u32 v202, v127, 4, 6
	v_lshlrev_b64 v[2:3], 14, v[2:3]
	v_lshlrev_b64 v[12:13], 14, v[12:13]
	v_ashrrev_i32_e32 v194, 10, v0
	v_lshl_add_u64 v[2:3], s[84:85], 0, v[2:3]
	v_lshlrev_b32_e32 v10, 8, v202
	v_mov_b32_e32 v11, v1
	v_lshl_add_u64 v[12:13], s[84:85], 0, v[12:13]
	v_bfe_u32 v201, v0, 4, 6
	v_add_u32_e32 v0, s0, v194
	v_lshl_add_u64 v[2:3], v[2:3], 0, v[10:11]
	v_lshl_add_u64 v[10:11], v[12:13], 0, v[10:11]
	v_lshl_or_b32 v12, v0, 5, s95
	v_ashrrev_i32_e32 v5, 31, v4
	v_ashrrev_i32_e32 v13, 31, v12
	v_lshlrev_b64 v[4:5], 14, v[4:5]
	v_lshlrev_b64 v[12:13], 14, v[12:13]
	v_lshl_add_u64 v[4:5], s[84:85], 0, v[4:5]
	v_lshlrev_b32_e32 v6, 8, v203
	v_mov_b32_e32 v7, v1
	v_lshl_add_u64 v[12:13], s[84:85], 0, v[12:13]
	v_lshlrev_b32_e32 v14, 8, v201
	v_mov_b32_e32 v15, v1
	v_mov_b32_e32 v133, v1
	v_lshl_add_u64 v[4:5], v[4:5], 0, v[6:7]
	v_lshl_add_u64 v[12:13], v[12:13], 0, v[14:15]
	v_lshl_add_u64 v[2:3], v[2:3], 0, v[132:133]
	v_lshl_add_u64 v[6:7], v[4:5], 0, v[132:133]
	v_lshl_add_u64 v[10:11], v[10:11], 0, v[132:133]
	v_lshl_add_u64 v[14:15], v[12:13], 0, v[132:133]
	global_load_dwordx4 v[2:5], v[2:3], off
	s_nop 0
	global_load_dwordx4 v[6:9], v[6:7], off
	s_nop 0
	global_load_dwordx4 v[10:13], v[10:11], off
	s_nop 0
	global_load_dwordx4 v[14:17], v[14:15], off
	v_and_b32_e32 v63, 15, v127
	v_lshrrev_b32_e32 v18, 2, v127
	v_and_or_b32 v171, v18, 48, v63
	s_mov_b32 s1, 0x8c00
	s_movk_i32 s3, 0x110
	v_and_b32_e32 v64, 48, v127
	v_mad_i32_i24 v18, v197, s1, 0
	v_mul_u32_u24_e32 v20, 0x110, v202
	v_mad_u32_u24 v21, v171, s3, 0
	v_add_u32_e32 v189, 0, v64
	v_mad_i32_i24 v22, v195, s1, 0
	v_mul_u32_u24_e32 v23, 0x110, v203
	v_mad_i32_i24 v24, v196, s1, 0
	v_mad_i32_i24 v25, v194, s1, 0
	v_mul_u32_u24_e32 v26, 0x110, v201
	v_add3_u32 v200, v18, v20, v132
	v_add_u32_e32 v190, v21, v64
	v_add3_u32 v199, v22, v23, v132
	v_add3_u32 v198, v24, v20, v132
	v_add3_u32 v191, v25, v26, v132
	v_mad_u32_u24 v67, v63, s3, v189
	v_ashrrev_i32_e32 v126, 8, v127
	v_and_b32_e32 v19, 0xffffff00, v127
	v_mad_i32_i24 v65, v126, s1, 0
	s_add_i32 s1, 0, 0x1a400
	s_add_i32 s0, 0, 0x1a000
	v_add3_u32 v187, s0, v64, v19
	v_bfe_u32 v0, v127, 4, 2
	v_lshlrev_b32_e32 v168, 2, v0
	v_cmp_gt_u32_e64 s[68:69], v168, v171
	v_cmp_lt_u32_e64 s[70:71], v168, v171
	s_movk_i32 s2, 0x90
	v_lshlrev_b32_e32 v0, 3, v0
	v_mad_u32_u24 v66, v171, s2, v65
	v_add_u32_e32 v184, v66, v0
	s_mov_b32 s78, s20
	v_mul_u32_u24_e32 v193, 0x110, v63
	v_add3_u32 v182, v65, v64, v193
	v_add_u32_e32 v188, v66, v64
	v_or_b32_e32 v128, s26, v171
	v_ashrrev_i32_e32 v129, 31, v128
	v_add_u32_e32 v183, 0xa800, v184
	v_mov_b32_e32 v206, v163
	s_waitcnt vmcnt(3)
	ds_write_b128 v200, v[2:5] offset:53248
	s_waitcnt vmcnt(2)
	ds_write_b128 v199, v[6:9] offset:53248
	s_waitcnt vmcnt(1)
	ds_write_b128 v198, v[10:13] offset:53248
	s_waitcnt vmcnt(0)
	ds_write_b128 v191, v[14:17] offset:53248
	s_waitcnt lgkmcnt(0)
	s_barrier
	ds_read_b128 v[38:41], v190
	ds_read_b128 v[34:37], v190 offset:64
	ds_read_b128 v[30:33], v190 offset:128
	ds_read_b128 v[26:29], v190 offset:192
	ds_read_b128 v[2:5], v67 offset:17408
	s_waitcnt lgkmcnt(0)
	v_mfma_f32_16x16x32_bf16 v[2:5], v[2:5], v[38:41], 0
	v_add_u32_e32 v6, s1, v19
	v_lshl_add_u32 v192, v171, 2, v6
	v_add_u32_e32 v186, v6, v64
	ds_read_b128 v[6:9], v67 offset:17472
	ds_read_b128 v[10:13], v67 offset:17536
	ds_read_b32 v133, v192
	ds_read_b128 v[14:17], v186
	ds_read_b128 v[18:21], v187 offset:64
	s_waitcnt lgkmcnt(4)
	v_mfma_f32_16x16x32_bf16 v[2:5], v[6:9], v[34:37], v[2:5]
	ds_read_b128 v[22:25], v67 offset:17600
	ds_read_b128 v[42:45], v67 offset:21760
	ds_read_b128 v[46:49], v67 offset:21824
	ds_read_b128 v[50:53], v67 offset:21888
	ds_read_b128 v[6:9], v67 offset:21952
	ds_read_b128 v[54:57], v187
	ds_read_b128 v[58:61], v186 offset:64
	s_waitcnt lgkmcnt(10)
	v_mfma_f32_16x16x32_bf16 v[2:5], v[10:13], v[30:33], v[2:5]
	s_waitcnt lgkmcnt(8)
	v_sub_f32_e32 v10, v133, v14
	v_mul_f32_e32 v10, 0x3fb8aa3b, v10
	v_exp_f32_e32 v10, v10
	s_waitcnt lgkmcnt(6)
	v_mfma_f32_16x16x32_bf16 v[2:5], v[22:25], v[26:29], v[2:5]
	v_or_b32_e32 v13, 3, v168
	v_cmp_gt_u32_e64 s[64:65], v13, v171
	s_nop 5
	v_mul_f32_e32 v2, v10, v2
	v_sub_f32_e32 v10, v133, v15
	v_mul_f32_e32 v10, 0x3fb8aa3b, v10
	v_exp_f32_e32 v10, v10
	s_waitcnt lgkmcnt(1)
	v_mul_f32_e32 v2, v54, v2
	v_cndmask_b32_e64 v11, v2, 0, s[68:69]
	v_mul_f32_e32 v2, v10, v3
	v_sub_f32_e32 v3, v133, v16
	v_mul_f32_e32 v3, 0x3fb8aa3b, v3
	v_exp_f32_e32 v3, v3
	v_mul_f32_e32 v2, v55, v2
	v_cndmask_b32_e64 v10, 0, v2, s[70:71]
	v_or_b32_e32 v2, 2, v168
	v_mul_f32_e32 v3, v3, v4
	v_sub_f32_e32 v4, v133, v17
	v_mul_f32_e32 v4, 0x3fb8aa3b, v4
	v_exp_f32_e32 v4, v4
	v_mul_f32_e32 v3, v56, v3
	v_cmp_gt_u32_e64 s[66:67], v2, v171
	v_cvt_pk_bf16_f32 v10, v11, v10
	v_mul_f32_e32 v2, v4, v5
	v_mul_f32_e32 v14, v57, v2
	v_cndmask_b32_e64 v12, v3, 0, s[66:67]
	v_mfma_f32_16x16x32_bf16 v[2:5], v[42:45], v[38:41], 0
	v_cndmask_b32_e64 v13, v14, 0, s[64:65]
	v_cvt_pk_bf16_f32 v11, v12, v13
	ds_write_b64 v184, v[10:11] offset:34816
	v_mfma_f32_16x16x32_bf16 v[2:5], v[46:49], v[34:37], v[2:5]
	s_waitcnt lgkmcnt(1)
; #define LAS __attribute__((address_space(3)))
; __device__ __forceinline__ unsigned pk2(float lo, float hi) { unsigned r; asm volatile("v_cvt_pk_bf16_f32 %0, %1, %2" : "=v"(r) : "v"(lo), "v"(hi)); return r; }
; __device__ __forceinline__ float fexp_(float x) { return __builtin_amdgcn_exp2f(x * 1.44269504089f); }
; #define MFMA(X, Y, C) __builtin_amdgcn_mfma_f32_16x16x32_bf16((X), (Y), (C), 0, 0, 0)
; __device__ void ssd_m2(const Params& p, LAS unsigned char* lds, int l, int b, int c, int g) {
;     ...
; #pragma unroll
;             for (int q = 0; q < 2; ++q) {
;                 const int jt = 2 * jh + q;
;                 f32x4 sc = {0.f, 0.f, 0.f, 0.f};
; #pragma unroll
;                 for (int kk = 0; kk < 4; ++kk) sc = MFMA(Xb[q][kk], Yc[kk], sc);
;                 float v[4];
; #pragma unroll
;                 for (int i = 0; i < 4; ++i) { const int j = jt * 16 + 4 * fq + i; v[i] = j <= irow ? sc[i] * fexp_(cumi - cj[q][i]) * dj[q][i] : 0.f; }
;                 u32x2 w; w.x = pk2(v[0], v[1]); w.y = pk2(v[2], v[3]);
;                 *(LAS u32x2*)(P + irow * 72 + jt * 16 + 4 * fq) = w;
;             }
;         }
	v_sub_f32_e32 v10, v133, v58
	v_mul_f32_e32 v10, 0x3fb8aa3b, v10
	v_exp_f32_e32 v10, v10
	v_mfma_f32_16x16x32_bf16 v[2:5], v[50:53], v[30:33], v[2:5]
	v_mfma_f32_16x16x32_bf16 v[2:5], v[6:9], v[26:29], v[2:5]
	v_sub_f32_e32 v7, v133, v59
	v_mul_f32_e32 v7, 0x3fb8aa3b, v7
	v_exp_f32_e32 v7, v7
	v_or_b32_e32 v6, 16, v168
	v_cmp_gt_u32_e64 s[62:63], v6, v171
	v_or_b32_e32 v6, 17, v168
	s_nop 1
	v_mul_f32_e32 v3, v7, v3
	v_sub_f32_e32 v7, v133, v60
	v_mul_f32_e32 v7, 0x3fb8aa3b, v7
	v_exp_f32_e32 v7, v7
	v_mul_f32_e32 v2, v10, v2
	v_cmp_gt_u32_e64 s[58:59], v6, v171
	v_or_b32_e32 v6, 18, v168
	v_mul_f32_e32 v4, v7, v4
	v_sub_f32_e32 v7, v133, v61
	v_mul_f32_e32 v7, 0x3fb8aa3b, v7
	v_exp_f32_e32 v7, v7
	v_mul_f32_e32 v2, v18, v2
	v_mul_f32_e32 v3, v19, v3
	v_cmp_gt_u32_e64 s[60:61], v6, v171
	v_or_b32_e32 v6, 19, v168
	v_mul_f32_e32 v5, v7, v5
	v_cndmask_b32_e64 v2, v2, 0, s[62:63]
	v_cndmask_b32_e64 v3, v3, 0, s[58:59]
	v_mul_f32_e32 v4, v20, v4
	v_mul_f32_e32 v5, v21, v5
	v_cmp_gt_u32_e64 s[56:57], v6, v171
	v_cndmask_b32_e64 v4, v4, 0, s[60:61]
	v_cvt_pk_bf16_f32 v2, v2, v3
	s_nop 0
	v_cndmask_b32_e64 v5, v5, 0, s[56:57]
	v_cvt_pk_bf16_f32 v3, v4, v5
	ds_write_b64 v184, v[2:3] offset:34848
	ds_read_b128 v[2:5], v67 offset:26112
	ds_read_b128 v[6:9], v67 offset:26176
	s_waitcnt lgkmcnt(1)
	v_mfma_f32_16x16x32_bf16 v[2:5], v[2:5], v[38:41], 0
	ds_read_b128 v[10:13], v67 offset:26240
	ds_read_b128 v[14:17], v67 offset:26304
	ds_read_b128 v[18:21], v67 offset:30464
	ds_read_b128 v[22:25], v67 offset:30528
	ds_read_b128 v[42:45], v67 offset:30592
	ds_read_b128 v[46:49], v67 offset:30656
	s_waitcnt lgkmcnt(6)
	v_mfma_f32_16x16x32_bf16 v[2:5], v[6:9], v[34:37], v[2:5]
	ds_read_b128 v[6:9], v186 offset:128
	ds_read_b128 v[50:53], v186 offset:192
	ds_read_b128 v[54:57], v187 offset:128
	ds_read_b128 v[58:61], v187 offset:192
	s_waitcnt lgkmcnt(3)
	v_sub_f32_e32 v6, v133, v6
	v_mfma_f32_16x16x32_bf16 v[2:5], v[10:13], v[30:33], v[2:5]
	v_mul_f32_e32 v6, 0x3fb8aa3b, v6
	v_exp_f32_e32 v6, v6
	v_or_b32_e32 v10, 32, v168
	v_mfma_f32_16x16x32_bf16 v[2:5], v[14:17], v[26:29], v[2:5]
	v_cmp_gt_u32_e64 s[84:85], v10, v171
	v_and_b32_e32 v14, 24, v62
	v_add_u32_e32 v185, v65, v14
	s_nop 4
	v_mul_f32_e32 v2, v6, v2
	v_sub_f32_e32 v6, v133, v7
	v_mul_f32_e32 v6, 0x3fb8aa3b, v6
	v_exp_f32_e32 v6, v6
	s_waitcnt lgkmcnt(1)
	v_mul_f32_e32 v2, v54, v2
	v_cndmask_b32_e64 v7, v2, 0, s[84:85]
	v_or_b32_e32 v2, 33, v168
	v_mul_f32_e32 v3, v6, v3
	v_sub_f32_e32 v6, v133, v8
	v_mul_f32_e32 v6, 0x3fb8aa3b, v6
	v_exp_f32_e32 v6, v6
	v_mul_f32_e32 v3, v55, v3
	v_cmp_gt_u32_e64 s[0:1], v2, v171
	v_or_b32_e32 v2, 34, v168
	v_cmp_gt_u32_e64 s[20:21], v2, v171
	v_writelane_b32 v255, s0, 1
	s_nop 1
	v_cndmask_b32_e64 v8, v3, 0, s[0:1]
	v_mul_f32_e32 v3, v6, v4
	v_sub_f32_e32 v4, v133, v9
	v_mul_f32_e32 v4, 0x3fb8aa3b, v4
	v_exp_f32_e32 v4, v4
	v_mul_f32_e32 v3, v56, v3
	v_cndmask_b32_e64 v9, v3, 0, s[20:21]
	v_or_b32_e32 v6, 35, v168
	v_mul_f32_e32 v10, v4, v5
	v_mfma_f32_16x16x32_bf16 v[2:5], v[18:21], v[38:41], 0
	v_mul_f32_e32 v10, v57, v10
	v_cmp_gt_u32_e64 s[88:89], v6, v171
	v_cvt_pk_bf16_f32 v6, v7, v8
	v_mfma_f32_16x16x32_bf16 v[2:5], v[22:25], v[34:37], v[2:5]
	v_writelane_b32 v255, s1, 2
	v_cndmask_b32_e64 v10, v10, 0, s[88:89]
	v_cvt_pk_bf16_f32 v7, v9, v10
	v_mfma_f32_16x16x32_bf16 v[2:5], v[42:45], v[30:33], v[2:5]
	ds_write_b64 v184, v[6:7] offset:34880
	v_sub_f32_e32 v6, v133, v50
	v_mul_f32_e32 v6, 0x3fb8aa3b, v6
	v_exp_f32_e32 v6, v6
	v_mfma_f32_16x16x32_bf16 v[2:5], v[46:49], v[26:29], v[2:5]
	v_or_b32_e32 v7, 48, v168
	v_cmp_gt_u32_e64 s[72:73], v7, v171
	v_or_b32_e32 v7, 49, v168
	v_cmp_gt_u32_e64 s[76:77], v7, v171
	v_or_b32_e32 v7, 50, v168
	s_nop 2
	v_mul_f32_e32 v2, v6, v2
	v_sub_f32_e32 v6, v133, v51
	v_mul_f32_e32 v6, 0x3fb8aa3b, v6
	v_exp_f32_e32 v6, v6
	s_waitcnt lgkmcnt(1)
	v_mul_f32_e32 v2, v58, v2
	v_cmp_gt_u32_e64 s[80:81], v7, v171
	v_or_b32_e32 v7, 51, v168
	v_mul_f32_e32 v3, v6, v3
	v_sub_f32_e32 v6, v133, v52
	v_mul_f32_e32 v6, 0x3fb8aa3b, v6
	v_exp_f32_e32 v6, v6
	v_mul_f32_e32 v3, v59, v3
	v_cndmask_b32_e64 v2, v2, 0, s[72:73]
	v_cndmask_b32_e64 v3, v3, 0, s[76:77]
	v_mul_f32_e32 v4, v6, v4
	v_sub_f32_e32 v6, v133, v53
	v_mul_f32_e32 v6, 0x3fb8aa3b, v6
	v_exp_f32_e32 v6, v6
	v_mul_f32_e32 v4, v60, v4
	v_cmp_gt_u32_e64 s[0:1], v7, v171
	v_cndmask_b32_e64 v4, v4, 0, s[80:81]
	v_mul_f32_e32 v5, v6, v5
	v_mul_f32_e32 v5, v61, v5
	v_writelane_b32 v254, s0, 54
	v_cvt_pk_bf16_f32 v2, v2, v3
	v_bfe_u32 v10, v127, 2, 2
	v_or_b32_e32 v204, v0, v10
	v_cndmask_b32_e64 v5, v5, 0, s[0:1]
	v_cvt_pk_bf16_f32 v3, v4, v5
	ds_write_b64 v184, v[2:3] offset:34912
	s_waitcnt lgkmcnt(0)
	s_barrier
; __device__ __forceinline__ float fexp_(float x) { return __builtin_amdgcn_exp2f(x * 1.44269504089f); }
; #define MFMA(X, Y, C) __builtin_amdgcn_mfma_f32_16x16x32_bf16((X), (Y), (C), 0, 0, 0)
; __device__ void ssd_m2(const Params& p, LAS unsigned char* lds, int l, int b, int c, int g) {
;     ...
;         u32x2 zraw[4];
; #pragma unroll
;         for (int pt = 0; pt < 4; ++pt) zraw[pt] = *(const u32x2*)(proj + t * NPROJ + PC_Z + h * 64 + pt * 16 + 4 * fq);
;         bf16x8 Yp[2];
; #pragma unroll
;         for (int kk = 0; kk < 2; ++kk) Yp[kk] = frag_row(P, 72, i0, kk * 32, fr, fq);
;         const float ecum = fexp_(cumi), Dh = p.in[22][l * 8 + h];
; #pragma unroll
;         for (int pt = 0; pt < 4; ++pt) {
;             f32x4 a1 = {0.f, 0.f, 0.f, 0.f}, a2 = {0.f, 0.f, 0.f, 0.f};
; #pragma unroll
;             for (int kk = 0; kk < 2; ++kk) a1 = MFMA(frag_tr(X, 72, kk * 32, pt * 16, fr, fq), Yp[kk], a1);
; #pragma unroll
;             for (int kk = 0; kk < 4; ++kk) a2 = MFMA(frag_row(S, 136, pt * 16, kk * 32, fr, fq), Yc[kk], a2);
	ds_read_b128 v[2:5], v182 offset:53248
	ds_read_b128 v[6:9], v182 offset:53312
	ds_read_b128 v[10:13], v182 offset:53376
	ds_read_b128 v[14:17], v182 offset:53440
	s_waitcnt lgkmcnt(3)
	v_mfma_f32_16x16x32_bf16 v[2:5], v[2:5], v[38:41], 0
	v_mad_u32_u24 v58, v204, s2, v185
	v_writelane_b32 v254, s1, 55
	s_mov_b64 s[0:1], 0x1400
	s_waitcnt lgkmcnt(2)
	v_mfma_f32_16x16x32_bf16 v[2:5], v[6:9], v[34:37], v[2:5]
	ds_read_b64_tr_b16 v[8:9], v58 offset:44608
	ds_read_b64_tr_b16 v[6:7], v58 offset:44032
	v_readlane_b32 s40, v254, 16
	v_readlane_b32 s52, v254, 28
	s_waitcnt lgkmcnt(3)
	v_mfma_f32_16x16x32_bf16 v[2:5], v[10:13], v[30:33], v[2:5]
	ds_read_b128 v[42:45], v188 offset:34816
	ds_read_b64_tr_b16 v[10:11], v58 offset:48640
	ds_read_b64_tr_b16 v[12:13], v58 offset:49216
	ds_read_b128 v[46:49], v188 offset:34880
	ds_read_b128 v[18:21], v182 offset:57728
	s_waitcnt lgkmcnt(7)
	v_mfma_f32_16x16x32_bf16 v[2:5], v[14:17], v[26:29], v[2:5]
	ds_read_b128 v[14:17], v182 offset:57600
	v_readlane_b32 s53, v254, 29
	v_readlane_b32 s41, v254, 17
	s_waitcnt lgkmcnt(5)
	v_mfma_f32_16x16x32_bf16 v[6:9], v[6:9], v[42:45], 0
	v_readlane_b32 s42, v254, 18
	v_readlane_b32 s43, v254, 19
	v_readlane_b32 s44, v254, 20
	s_waitcnt lgkmcnt(2)
	v_mfma_f32_16x16x32_bf16 v[6:9], v[10:13], v[46:49], v[6:9]
	ds_read_b128 v[10:13], v182 offset:57664
	v_readlane_b32 s45, v254, 21
	v_readlane_b32 s46, v254, 22
	s_waitcnt lgkmcnt(1)
	v_mfma_f32_16x16x32_bf16 v[14:17], v[14:17], v[38:41], 0
	v_readlane_b32 s47, v254, 23
	v_readlane_b32 s48, v254, 24
	v_readlane_b32 s49, v254, 25
	s_waitcnt lgkmcnt(0)
	v_mfma_f32_16x16x32_bf16 v[10:13], v[10:13], v[34:37], v[14:17]
	s_nop 2
	ds_read_b64_tr_b16 v[14:15], v58 offset:44064
	ds_read_b64_tr_b16 v[16:17], v58 offset:44640
	ds_read_b128 v[22:25], v182 offset:57792
	v_readlane_b32 s50, v254, 26
	v_readlane_b32 s51, v254, 27
	v_mfma_f32_16x16x32_bf16 v[10:13], v[18:21], v[30:33], v[10:13]
	v_lshlrev_b64 v[18:19], 13, v[128:129]
	v_lshl_add_u64 v[18:19], s[34:35], 0, v[18:19]
	v_lshl_add_u64 v[18:19], v[18:19], 0, v[0:1]
	v_add_u32_e32 v0, s94, v126
	v_lshl_add_u64 v[130:131], v[18:19], 0, s[0:1]
	v_lshlrev_b32_e32 v18, 6, v0
	v_ashrrev_i32_e32 v19, 31, v18
	v_lshl_add_u64 v[18:19], v[18:19], 1, v[130:131]
	v_readlane_b32 s0, v254, 47
	global_load_dwordx2 v[140:141], v[18:19], off
	global_load_dwordx2 v[138:139], v[18:19], off offset:32
	global_load_dwordx2 v[136:137], v[18:19], off offset:64
	global_load_dwordx2 v[134:135], v[18:19], off offset:96
	v_add_u32_e32 v18, s0, v0
	v_ashrrev_i32_e32 v19, 31, v18
	v_lshl_add_u64 v[18:19], v[18:19], 2, s[52:53]
	global_load_dword v205, v[18:19], off
	ds_read_b64_tr_b16 v[18:19], v58 offset:48672
	ds_read_b64_tr_b16 v[20:21], v58 offset:49248
	s_waitcnt lgkmcnt(2)
	v_mfma_f32_16x16x32_bf16 v[10:13], v[22:25], v[26:29], v[10:13]
	ds_read_b128 v[22:25], v182 offset:61952
	ds_read_b128 v[50:53], v182 offset:62080
	v_add_u32_e32 v129, 0xd000, v182
	v_mfma_f32_16x16x32_bf16 v[14:17], v[14:17], v[42:45], 0
	s_movk_i32 s0, 0x7f
	v_readlane_b32 s54, v254, 30
	v_readlane_b32 s55, v254, 31
	s_waitcnt lgkmcnt(2)
	v_mfma_f32_16x16x32_bf16 v[14:17], v[18:21], v[46:49], v[14:17]
	ds_read_b128 v[18:21], v182 offset:62016
	s_waitcnt lgkmcnt(2)
	v_mfma_f32_16x16x32_bf16 v[22:25], v[22:25], v[38:41], 0
	s_waitcnt lgkmcnt(0)
	v_mfma_f32_16x16x32_bf16 v[18:21], v[18:21], v[34:37], v[22:25]
	s_nop 5
	ds_read_b128 v[22:25], v182 offset:62144
	ds_read_b64_tr_b16 v[54:55], v58 offset:44096
	v_mfma_f32_16x16x32_bf16 v[18:21], v[50:53], v[30:33], v[18:21]
	ds_read_b64_tr_b16 v[56:57], v58 offset:44672
	ds_read_b64_tr_b16 v[50:51], v58 offset:48704
	ds_read_b64_tr_b16 v[52:53], v58 offset:49280
	s_waitcnt lgkmcnt(4)
	v_mfma_f32_16x16x32_bf16 v[18:21], v[22:25], v[26:29], v[18:21]
	s_waitcnt lgkmcnt(2)
	v_mfma_f32_16x16x32_bf16 v[22:25], v[54:57], v[42:45], 0
	ds_read_b128 v[54:57], v129 offset:13056
	s_waitcnt lgkmcnt(1)
	v_mfma_f32_16x16x32_bf16 v[22:25], v[50:53], v[46:49], v[22:25]
	ds_read_b128 v[50:53], v129 offset:13120
	s_waitcnt lgkmcnt(1)
	v_mfma_f32_16x16x32_bf16 v[38:41], v[54:57], v[38:41], 0
	ds_read_b128 v[54:57], v129 offset:13184
	s_waitcnt lgkmcnt(1)
	v_mfma_f32_16x16x32_bf16 v[34:37], v[50:53], v[34:37], v[38:41]
	s_nop 4
	ds_read_b128 v[38:41], v129 offset:13248
	ds_read_b64_tr_b16 v[50:51], v58 offset:44128
	s_waitcnt lgkmcnt(2)
	v_mfma_f32_16x16x32_bf16 v[30:33], v[54:57], v[30:33], v[34:37]
	ds_read_b64_tr_b16 v[52:53], v58 offset:44704
	ds_read_b64_tr_b16 v[54:55], v58 offset:48736
	ds_read_b64_tr_b16 v[56:57], v58 offset:49312
	s_waitcnt lgkmcnt(4)
	v_mfma_f32_16x16x32_bf16 v[26:29], v[38:41], v[26:29], v[30:33]
	ds_read2_b64 v[38:41], v183 offset0:128 offset1:132
	ds_read2_b64 v[34:37], v183 offset0:136 offset1:140
	s_waitcnt lgkmcnt(0)
	s_barrier
; #define LAS __attribute__((address_space(3)))
; #define TIDX opaque_tid()
; __device__ __forceinline__ u32x4 pack8(const float* f) { u32x4 w; w.x = pk2(f[0], f[1]); w.y = pk2(f[2], f[3]); w.z = pk2(f[4], f[5]); w.w = pk2(f[6], f[7]); return w; }
; template <class CM, class F>
; __device__ __forceinline__ void conv64(const bf16_t* proj, int row0, int tseq0, int pc0, const float* cw, const float* cb, int C, int nchunks, CM&& chmap, F&& emit) {
;     for (int u = TIDX; u < nchunks * 8; u += 512) {
;         const int q = u % nchunks, seg = u / nchunks, c = chmap(q), j0 = seg * 8;
;         const bf16_t* src = proj + (size_t)(row0 + j0) * NPROJ + pc0 + c;
;         u32x4 raw[11];
;         if (tseq0 + j0 == 0) { raw[0] = (u32x4){0u, 0u, 0u, 0u}; raw[1] = raw[0]; raw[2] = raw[0]; }
;         else { raw[0] = *(const u32x4*)(src - 3 * NPROJ); raw[1] = *(const u32x4*)(src - 2 * NPROJ); raw[2] = *(const u32x4*)(src - NPROJ); }
; #pragma unroll
;         for (int j = 0; j < 8; ++j) raw[3 + j] = *(const u32x4*)(src + (size_t)j * NPROJ);
;         float w0[8], w1[8], w2[8], w3[8], bb[8];
; #pragma unroll
;         for (int e = 0; e < 8; ++e) { w0[e] = cw[c + e]; w1[e] = cw[C + c + e]; w2[e] = cw[2 * C + c + e]; w3[e] = cw[3 * C + c + e]; bb[e] = cb[c + e]; }
;         float h3[8], h2[8], h1[8];
;         unpack8(raw[0], h3); unpack8(raw[1], h2); unpack8(raw[2], h1);
; #pragma unroll
;         for (int j = 0; j < 8; ++j) {
;             float cur[8], y[8];
;             unpack8(raw[3 + j], cur);
; #pragma unroll
;             for (int e = 0; e < 8; ++e) y[e] = bb[e] + w0[e] * h3[e] + w1[e] * h2[e] + w2[e] * h1[e] + w3[e] * cur[e];
;             emit(j0 + j, q, c, y);
; #pragma unroll
;             for (int e = 0; e < 8; ++e) { h3[e] = h2[e]; h2[e] = h1[e]; h1[e] = cur[e]; }
;         }
; __device__ void ssd_m2(const Params& p, LAS unsigned char* lds, int l, int b, int c, int g) {
;     ...
;         conv64(proj, row0, c * 64, PC_XBC, cw, cb, 1024, 16, [hbase](int q) { return hbase * 64 + q * 8; },
;                [&](int j, int q, int ch, float* y) {
;                    float s[8];
; #pragma unroll
;                    for (int e = 0; e < 8; ++e) s[e] = siluf_(y[e]);
;                    *(LAS u32x4*)((LAS bf16_t*)(lds + PB + (q >> 3) * HB + 9216) + j * 72 + (q & 7) * 8) = pack8(s);
;                });
	v_mfma_f32_16x16x32_bf16 v[30:33], v[50:53], v[42:45], 0
	v_mfma_f32_16x16x32_bf16 v[30:33], v[54:57], v[46:49], v[30:33]
	v_cmp_lt_i32_e32 vcc, s0, v206
	s_and_saveexec_b64 s[0:1], vcc
	s_xor_b64 s[0:1], exec, s[0:1]
	s_lshl_b32 s2, s96, 8
	s_or_saveexec_b64 s[0:1], s[0:1]
	v_mov_b32_e32 v42, s2
	v_and_b32_e32 v43, 15, v163
	v_lshrrev_b32_e32 v0, 4, v163
	v_lshlrev_b32_e32 v0, 1, v0
	s_lshl_b32 s36, s96, 8
	s_or_b32 s36, s36, 0x80
	v_lshl_add_u32 v112, v43, 3, s36
	v_add_u32_e32 v113, s30, v0
	v_add_u32_e32 v104, s26, v0
	v_add_u32_e32 v104, -3, v104
	v_ashrrev_i32_e32 v105, 31, v104
	v_lshlrev_b64 v[104:105], 13, v[104:105]
	v_lshl_add_u64 v[104:105], s[34:35], 0, v[104:105]
	v_lshlrev_b32_e32 v114, 1, v112
	v_mov_b32_e32 v115, 0
	v_lshl_add_u64 v[104:105], v[104:105], 0, v[114:115]
	s_mov_b64 s[40:41], 0x1800
	v_lshl_add_u64 v[104:105], v[104:105], 0, s[40:41]
	v_lshlrev_b32_e32 v114, 2, v112
	v_lshl_add_u64 v[106:107], s[22:23], 0, v[114:115]
	v_lshl_add_u64 v[108:109], s[38:39], 0, v[114:115]
	v_mov_b32_e32 v44, 0
	v_mov_b32_e32 v45, 0
	v_mov_b32_e32 v46, 0
	v_mov_b32_e32 v47, 0
	v_mov_b32_e32 v48, 0
	v_mov_b32_e32 v49, 0
	v_mov_b32_e32 v50, 0
	v_mov_b32_e32 v51, 0
	v_mov_b32_e32 v52, 0
	v_mov_b32_e32 v53, 0
	v_mov_b32_e32 v54, 0
	v_mov_b32_e32 v55, 0
	s_mov_b64 s[40:41], 0x2000
	v_cmp_le_i32_e32 vcc, 3, v113
	s_and_saveexec_b64 s[36:37], vcc
	global_load_dwordx4 v[44:47], v[104:105], off
	s_or_b64 exec, exec, s[36:37]
	v_lshl_add_u64 v[104:105], v[104:105], 0, s[40:41]
	v_cmp_le_i32_e32 vcc, 2, v113
	s_and_saveexec_b64 s[36:37], vcc
	global_load_dwordx4 v[48:51], v[104:105], off
	s_or_b64 exec, exec, s[36:37]
	v_lshl_add_u64 v[104:105], v[104:105], 0, s[40:41]
	v_cmp_le_i32_e32 vcc, 1, v113
	s_and_saveexec_b64 s[36:37], vcc
	global_load_dwordx4 v[52:55], v[104:105], off
	s_or_b64 exec, exec, s[36:37]
	v_lshl_add_u64 v[104:105], v[104:105], 0, s[40:41]
	global_load_dwordx4 v[56:59], v[104:105], off
	v_lshl_add_u64 v[104:105], v[104:105], 0, s[40:41]
	global_load_dwordx4 v[60:63], v[104:105], off
	s_mov_b64 s[40:41], 0x1000
	global_load_dwordx4 v[64:67], v[106:107], off
	global_load_dwordx4 v[68:71], v[106:107], off offset:16
	v_lshl_add_u64 v[106:107], v[106:107], 0, s[40:41]
	global_load_dwordx4 v[72:75], v[106:107], off
	global_load_dwordx4 v[76:79], v[106:107], off offset:16
	v_lshl_add_u64 v[106:107], v[106:107], 0, s[40:41]
	global_load_dwordx4 v[80:83], v[106:107], off
	global_load_dwordx4 v[84:87], v[106:107], off offset:16
	v_lshl_add_u64 v[106:107], v[106:107], 0, s[40:41]
	global_load_dwordx4 v[88:91], v[106:107], off
	global_load_dwordx4 v[92:95], v[106:107], off offset:16
	global_load_dwordx4 v[96:99], v[108:109], off
	global_load_dwordx4 v[100:103], v[108:109], off offset:16
	v_lshrrev_b32_e32 v116, 3, v43
	v_mul_u32_u24_e32 v116, 0x8c00, v116
	v_mul_u32_u24_e32 v114, 0x90, v0
	v_and_b32_e32 v115, 7, v43
	v_lshl_add_u32 v114, v115, 4, v114
	v_add_u32_e32 v116, v116, v114
	s_waitcnt vmcnt(0)
	v_lshlrev_b32_e32 v114, 16, v44
	v_mul_f32_e32 v114, v64, v114
	v_add_f32_e32 v112, v96, v114
	v_lshlrev_b32_e32 v114, 16, v48
	v_mul_f32_e32 v114, v72, v114
	v_add_f32_e32 v112, v112, v114
	v_lshlrev_b32_e32 v114, 16, v52
	v_mul_f32_e32 v114, v80, v114
	v_add_f32_e32 v112, v112, v114
	v_lshlrev_b32_e32 v114, 16, v56
	v_mul_f32_e32 v114, v88, v114
	v_add_f32_e32 v112, v112, v114
	v_lshlrev_b32_e32 v115, 16, v48
	v_mul_f32_e32 v115, v64, v115
	v_add_f32_e32 v113, v96, v115
	v_lshlrev_b32_e32 v115, 16, v52
	v_mul_f32_e32 v115, v72, v115
	v_add_f32_e32 v113, v113, v115
	v_lshlrev_b32_e32 v115, 16, v56
	v_mul_f32_e32 v115, v80, v115
	v_add_f32_e32 v113, v113, v115
	v_lshlrev_b32_e32 v115, 16, v60
	v_mul_f32_e32 v115, v88, v115
	v_add_f32_e32 v113, v113, v115
	v_mul_f32_e32 v114, 0xbfb8aa3b, v112
	v_mul_f32_e32 v115, 0xbfb8aa3b, v113
	v_exp_f32_e32 v114, v114
	v_exp_f32_e32 v115, v115
	s_nop 0
	v_add_f32_e32 v114, 1.0, v114
	v_add_f32_e32 v115, 1.0, v115
	v_rcp_f32_e32 v114, v114
	v_rcp_f32_e32 v115, v115
	s_nop 0
	v_mul_f32_e32 v117, v112, v114
	v_mul_f32_e32 v43, v113, v115
	v_and_b32_e32 v114, 0xffff0000, v44
	v_mul_f32_e32 v114, v65, v114
	v_add_f32_e32 v112, v97, v114
	v_and_b32_e32 v114, 0xffff0000, v48
	v_mul_f32_e32 v114, v73, v114
	v_add_f32_e32 v112, v112, v114
	v_and_b32_e32 v114, 0xffff0000, v52
	v_mul_f32_e32 v114, v81, v114
	v_add_f32_e32 v112, v112, v114
	v_and_b32_e32 v114, 0xffff0000, v56
	v_mul_f32_e32 v114, v89, v114
	v_add_f32_e32 v112, v112, v114
	v_and_b32_e32 v115, 0xffff0000, v48
	v_mul_f32_e32 v115, v65, v115
	v_add_f32_e32 v113, v97, v115
	v_and_b32_e32 v115, 0xffff0000, v52
	v_mul_f32_e32 v115, v73, v115
	v_add_f32_e32 v113, v113, v115
	v_and_b32_e32 v115, 0xffff0000, v56
	v_mul_f32_e32 v115, v81, v115
	v_add_f32_e32 v113, v113, v115
	v_and_b32_e32 v115, 0xffff0000, v60
	v_mul_f32_e32 v115, v89, v115
	v_add_f32_e32 v113, v113, v115
	v_mul_f32_e32 v114, 0xbfb8aa3b, v112
	v_mul_f32_e32 v115, 0xbfb8aa3b, v113
	v_exp_f32_e32 v114, v114
	v_exp_f32_e32 v115, v115
	s_nop 0
	v_add_f32_e32 v114, 1.0, v114
	v_add_f32_e32 v115, 1.0, v115
	v_rcp_f32_e32 v114, v114
	v_rcp_f32_e32 v115, v115
	s_nop 0
	v_mul_f32_e32 v112, v112, v114
	v_mul_f32_e32 v113, v113, v115
	v_cvt_pk_bf16_f32 v104, v117, v112
	v_cvt_pk_bf16_f32 v108, v43, v113
	v_lshlrev_b32_e32 v114, 16, v45
	v_mul_f32_e32 v114, v66, v114
	v_add_f32_e32 v112, v98, v114
	v_lshlrev_b32_e32 v114, 16, v49
	v_mul_f32_e32 v114, v74, v114
	v_add_f32_e32 v112, v112, v114
	v_lshlrev_b32_e32 v114, 16, v53
	v_mul_f32_e32 v114, v82, v114
	v_add_f32_e32 v112, v112, v114
	v_lshlrev_b32_e32 v114, 16, v57
	v_mul_f32_e32 v114, v90, v114
	v_add_f32_e32 v112, v112, v114
; #define LAS __attribute__((address_space(3)))
; #define TIDX opaque_tid()
; __device__ __forceinline__ u32x4 pack8(const float* f) { u32x4 w; w.x = pk2(f[0], f[1]); w.y = pk2(f[2], f[3]); w.z = pk2(f[4], f[5]); w.w = pk2(f[6], f[7]); return w; }
; template <class CM, class F>
; __device__ __forceinline__ void conv64(const bf16_t* proj, int row0, int tseq0, int pc0, const float* cw, const float* cb, int C, int nchunks, CM&& chmap, F&& emit) {
;     for (int u = TIDX; u < nchunks * 8; u += 512) {
;         const int q = u % nchunks, seg = u / nchunks, c = chmap(q), j0 = seg * 8;
;         const bf16_t* src = proj + (size_t)(row0 + j0) * NPROJ + pc0 + c;
;         u32x4 raw[11];
;         if (tseq0 + j0 == 0) { raw[0] = (u32x4){0u, 0u, 0u, 0u}; raw[1] = raw[0]; raw[2] = raw[0]; }
;         else { raw[0] = *(const u32x4*)(src - 3 * NPROJ); raw[1] = *(const u32x4*)(src - 2 * NPROJ); raw[2] = *(const u32x4*)(src - NPROJ); }
; #pragma unroll
;         for (int j = 0; j < 8; ++j) raw[3 + j] = *(const u32x4*)(src + (size_t)j * NPROJ);
;         float w0[8], w1[8], w2[8], w3[8], bb[8];
; #pragma unroll
;         for (int e = 0; e < 8; ++e) { w0[e] = cw[c + e]; w1[e] = cw[C + c + e]; w2[e] = cw[2 * C + c + e]; w3[e] = cw[3 * C + c + e]; bb[e] = cb[c + e]; }
;         float h3[8], h2[8], h1[8];
;         unpack8(raw[0], h3); unpack8(raw[1], h2); unpack8(raw[2], h1);
; #pragma unroll
;         for (int j = 0; j < 8; ++j) {
;             float cur[8], y[8];
;             unpack8(raw[3 + j], cur);
; #pragma unroll
;             for (int e = 0; e < 8; ++e) y[e] = bb[e] + w0[e] * h3[e] + w1[e] * h2[e] + w2[e] * h1[e] + w3[e] * cur[e];
;             emit(j0 + j, q, c, y);
; #pragma unroll
;             for (int e = 0; e < 8; ++e) { h3[e] = h2[e]; h2[e] = h1[e]; h1[e] = cur[e]; }
;         }
; __device__ void ssd_m2(const Params& p, LAS unsigned char* lds, int l, int b, int c, int g) {
;     ...
;         conv64(proj, row0, c * 64, PC_XBC, cw, cb, 1024, 16, [hbase](int q) { return hbase * 64 + q * 8; },
;                [&](int j, int q, int ch, float* y) {
;                    float s[8];
; #pragma unroll
;                    for (int e = 0; e < 8; ++e) s[e] = siluf_(y[e]);
;                    *(LAS u32x4*)((LAS bf16_t*)(lds + PB + (q >> 3) * HB + 9216) + j * 72 + (q & 7) * 8) = pack8(s);
;                });
	v_lshlrev_b32_e32 v115, 16, v49
	v_mul_f32_e32 v115, v66, v115
	v_add_f32_e32 v113, v98, v115
	v_lshlrev_b32_e32 v115, 16, v53
	v_mul_f32_e32 v115, v74, v115
	v_add_f32_e32 v113, v113, v115
	v_lshlrev_b32_e32 v115, 16, v57
	v_mul_f32_e32 v115, v82, v115
	v_add_f32_e32 v113, v113, v115
	v_lshlrev_b32_e32 v115, 16, v61
	v_mul_f32_e32 v115, v90, v115
	v_add_f32_e32 v113, v113, v115
	v_mul_f32_e32 v114, 0xbfb8aa3b, v112
	v_mul_f32_e32 v115, 0xbfb8aa3b, v113
	v_exp_f32_e32 v114, v114
	v_exp_f32_e32 v115, v115
	s_nop 0
	v_add_f32_e32 v114, 1.0, v114
	v_add_f32_e32 v115, 1.0, v115
	v_rcp_f32_e32 v114, v114
	v_rcp_f32_e32 v115, v115
	s_nop 0
	v_mul_f32_e32 v117, v112, v114
	v_mul_f32_e32 v43, v113, v115
	v_and_b32_e32 v114, 0xffff0000, v45
	v_mul_f32_e32 v114, v67, v114
	v_add_f32_e32 v112, v99, v114
	v_and_b32_e32 v114, 0xffff0000, v49
	v_mul_f32_e32 v114, v75, v114
	v_add_f32_e32 v112, v112, v114
	v_and_b32_e32 v114, 0xffff0000, v53
	v_mul_f32_e32 v114, v83, v114
	v_add_f32_e32 v112, v112, v114
	v_and_b32_e32 v114, 0xffff0000, v57
	v_mul_f32_e32 v114, v91, v114
	v_add_f32_e32 v112, v112, v114
	v_and_b32_e32 v115, 0xffff0000, v49
	v_mul_f32_e32 v115, v67, v115
	v_add_f32_e32 v113, v99, v115
	v_and_b32_e32 v115, 0xffff0000, v53
	v_mul_f32_e32 v115, v75, v115
	v_add_f32_e32 v113, v113, v115
	v_and_b32_e32 v115, 0xffff0000, v57
	v_mul_f32_e32 v115, v83, v115
	v_add_f32_e32 v113, v113, v115
	v_and_b32_e32 v115, 0xffff0000, v61
	v_mul_f32_e32 v115, v91, v115
	v_add_f32_e32 v113, v113, v115
	v_mul_f32_e32 v114, 0xbfb8aa3b, v112
	v_mul_f32_e32 v115, 0xbfb8aa3b, v113
	v_exp_f32_e32 v114, v114
	v_exp_f32_e32 v115, v115
	s_nop 0
	v_add_f32_e32 v114, 1.0, v114
	v_add_f32_e32 v115, 1.0, v115
	v_rcp_f32_e32 v114, v114
	v_rcp_f32_e32 v115, v115
	s_nop 0
	v_mul_f32_e32 v112, v112, v114
	v_mul_f32_e32 v113, v113, v115
	v_cvt_pk_bf16_f32 v105, v117, v112
	v_cvt_pk_bf16_f32 v109, v43, v113
	v_lshlrev_b32_e32 v114, 16, v46
	v_mul_f32_e32 v114, v68, v114
	v_add_f32_e32 v112, v100, v114
	v_lshlrev_b32_e32 v114, 16, v50
	v_mul_f32_e32 v114, v76, v114
	v_add_f32_e32 v112, v112, v114
	v_lshlrev_b32_e32 v114, 16, v54
	v_mul_f32_e32 v114, v84, v114
	v_add_f32_e32 v112, v112, v114
	v_lshlrev_b32_e32 v114, 16, v58
	v_mul_f32_e32 v114, v92, v114
	v_add_f32_e32 v112, v112, v114
	v_lshlrev_b32_e32 v115, 16, v50
	v_mul_f32_e32 v115, v68, v115
	v_add_f32_e32 v113, v100, v115
	v_lshlrev_b32_e32 v115, 16, v54
	v_mul_f32_e32 v115, v76, v115
	v_add_f32_e32 v113, v113, v115
	v_lshlrev_b32_e32 v115, 16, v58
	v_mul_f32_e32 v115, v84, v115
	v_add_f32_e32 v113, v113, v115
	v_lshlrev_b32_e32 v115, 16, v62
	v_mul_f32_e32 v115, v92, v115
	v_add_f32_e32 v113, v113, v115
	v_mul_f32_e32 v114, 0xbfb8aa3b, v112
	v_mul_f32_e32 v115, 0xbfb8aa3b, v113
	v_exp_f32_e32 v114, v114
	v_exp_f32_e32 v115, v115
	s_nop 0
	v_add_f32_e32 v114, 1.0, v114
	v_add_f32_e32 v115, 1.0, v115
	v_rcp_f32_e32 v114, v114
	v_rcp_f32_e32 v115, v115
	s_nop 0
	v_mul_f32_e32 v117, v112, v114
	v_mul_f32_e32 v43, v113, v115
	v_and_b32_e32 v114, 0xffff0000, v46
	v_mul_f32_e32 v114, v69, v114
	v_add_f32_e32 v112, v101, v114
	v_and_b32_e32 v114, 0xffff0000, v50
	v_mul_f32_e32 v114, v77, v114
	v_add_f32_e32 v112, v112, v114
	v_and_b32_e32 v114, 0xffff0000, v54
	v_mul_f32_e32 v114, v85, v114
	v_add_f32_e32 v112, v112, v114
	v_and_b32_e32 v114, 0xffff0000, v58
	v_mul_f32_e32 v114, v93, v114
	v_add_f32_e32 v112, v112, v114
	v_and_b32_e32 v115, 0xffff0000, v50
	v_mul_f32_e32 v115, v69, v115
	v_add_f32_e32 v113, v101, v115
	v_and_b32_e32 v115, 0xffff0000, v54
	v_mul_f32_e32 v115, v77, v115
	v_add_f32_e32 v113, v113, v115
	v_and_b32_e32 v115, 0xffff0000, v58
	v_mul_f32_e32 v115, v85, v115
	v_add_f32_e32 v113, v113, v115
	v_and_b32_e32 v115, 0xffff0000, v62
	v_mul_f32_e32 v115, v93, v115
	v_add_f32_e32 v113, v113, v115
	v_mul_f32_e32 v114, 0xbfb8aa3b, v112
	v_mul_f32_e32 v115, 0xbfb8aa3b, v113
	v_exp_f32_e32 v114, v114
	v_exp_f32_e32 v115, v115
	s_nop 0
	v_add_f32_e32 v114, 1.0, v114
	v_add_f32_e32 v115, 1.0, v115
	v_rcp_f32_e32 v114, v114
	v_rcp_f32_e32 v115, v115
	s_nop 0
	v_mul_f32_e32 v112, v112, v114
	v_mul_f32_e32 v113, v113, v115
	v_cvt_pk_bf16_f32 v106, v117, v112
	v_cvt_pk_bf16_f32 v110, v43, v113
	v_lshlrev_b32_e32 v114, 16, v47
	v_mul_f32_e32 v114, v70, v114
	v_add_f32_e32 v112, v102, v114
	v_lshlrev_b32_e32 v114, 16, v51
	v_mul_f32_e32 v114, v78, v114
	v_add_f32_e32 v112, v112, v114
	v_lshlrev_b32_e32 v114, 16, v55
	v_mul_f32_e32 v114, v86, v114
	v_add_f32_e32 v112, v112, v114
	v_lshlrev_b32_e32 v114, 16, v59
	v_mul_f32_e32 v114, v94, v114
	v_add_f32_e32 v112, v112, v114
	v_lshlrev_b32_e32 v115, 16, v51
	v_mul_f32_e32 v115, v70, v115
	v_add_f32_e32 v113, v102, v115
	v_lshlrev_b32_e32 v115, 16, v55
	v_mul_f32_e32 v115, v78, v115
	v_add_f32_e32 v113, v113, v115
	v_lshlrev_b32_e32 v115, 16, v59
	v_mul_f32_e32 v115, v86, v115
	v_add_f32_e32 v113, v113, v115
	v_lshlrev_b32_e32 v115, 16, v63
	v_mul_f32_e32 v115, v94, v115
	v_add_f32_e32 v113, v113, v115
	v_mul_f32_e32 v114, 0xbfb8aa3b, v112
	v_mul_f32_e32 v115, 0xbfb8aa3b, v113
	v_exp_f32_e32 v114, v114
	v_exp_f32_e32 v115, v115
	s_nop 0
	v_add_f32_e32 v114, 1.0, v114
	v_add_f32_e32 v115, 1.0, v115
	v_rcp_f32_e32 v114, v114
	v_rcp_f32_e32 v115, v115
	s_nop 0
	v_mul_f32_e32 v117, v112, v114
	v_mul_f32_e32 v43, v113, v115
	v_and_b32_e32 v114, 0xffff0000, v47
	v_mul_f32_e32 v114, v71, v114
	v_add_f32_e32 v112, v103, v114
	v_and_b32_e32 v114, 0xffff0000, v51
	v_mul_f32_e32 v114, v79, v114
	v_add_f32_e32 v112, v112, v114
	v_and_b32_e32 v114, 0xffff0000, v55
	v_mul_f32_e32 v114, v87, v114
	v_add_f32_e32 v112, v112, v114
	v_and_b32_e32 v114, 0xffff0000, v59
	v_mul_f32_e32 v114, v95, v114
	v_add_f32_e32 v112, v112, v114
	v_and_b32_e32 v115, 0xffff0000, v51
	v_mul_f32_e32 v115, v71, v115
	v_add_f32_e32 v113, v103, v115
	v_and_b32_e32 v115, 0xffff0000, v55
	v_mul_f32_e32 v115, v79, v115
	v_add_f32_e32 v113, v113, v115
	v_and_b32_e32 v115, 0xffff0000, v59
	v_mul_f32_e32 v115, v87, v115
	v_add_f32_e32 v113, v113, v115
	v_and_b32_e32 v115, 0xffff0000, v63
	v_mul_f32_e32 v115, v95, v115
	v_add_f32_e32 v113, v113, v115
	v_mul_f32_e32 v114, 0xbfb8aa3b, v112
	v_mul_f32_e32 v115, 0xbfb8aa3b, v113
	v_exp_f32_e32 v114, v114
	v_exp_f32_e32 v115, v115
	s_nop 0
	v_add_f32_e32 v114, 1.0, v114
	v_add_f32_e32 v115, 1.0, v115
	v_rcp_f32_e32 v114, v114
	v_rcp_f32_e32 v115, v115
	s_nop 0
	v_mul_f32_e32 v112, v112, v114
	v_mul_f32_e32 v113, v113, v115
	v_cvt_pk_bf16_f32 v107, v117, v112
	v_cvt_pk_bf16_f32 v111, v43, v113
	ds_write_b128 v116, v[104:107] offset:44032
	ds_write_b128 v116, v[108:111] offset:44176
	s_waitcnt lgkmcnt(0)
	s_branch .LBB0_356
